# fast hand-written UP (relu^2) epilogue on the rsl path + placement check (XCD-local barriers only if every blockIdx%8 group sits on one XCC) on top of XCD-local barriers
# speedup vs baseline: 1.0100x; 1.0014x over previous
; #define LAS __attribute__((address_space(3)))
; __global__ void __launch_bounds__(NWAVES * 64, 2) trunk_fwd(Args args) {
;     extern __shared__ __attribute__((aligned(16))) unsigned char lds[];
;     cg::grid_group grid = cg::this_grid();
;     LAS unsigned char* L = (LAS unsigned char*)lds;
;     if (threadIdx.x == 0) { ((volatile LAS unsigned*)(L + XB_ST_OFF))[0] = 0u; ((volatile LAS unsigned*)(L + XB_ST_OFF))[1] = 0u; }
;     __syncthreads();
;     if (blockIdx.x == 0) for (int i = threadIdx.x; i < XCD_BAR_WORDS; i += NWAVES * 64) ((unsigned*)args.ws)[i] = 0u;
_Z9trunk_fwd4Args:
	s_add_u32 s8, s0, 0xe0
	v_writelane_b32 v255, s2, 0
	v_writelane_b32 v255, 1, 42
	s_load_dwordx4 s[80:83], s[0:1], 0xd0
	s_load_dwordx2 s[2:3], s[0:1], 0xe0
	s_load_dword s76, s[0:1], 0xe8
	v_and_b32_e32 v206, 0x3ff, v0
	s_waitcnt lgkmcnt(0)
	v_writelane_b32 v255, s2, 1
	s_nop 1
	v_writelane_b32 v255, s3, 2
	v_writelane_b32 v255, s0, 3
	s_addc_u32 s9, s1, 0
	s_nop 0
	v_writelane_b32 v255, s1, 4
	v_cmp_eq_u32_e64 s[0:1], 0, v206
	s_nop 1
	v_writelane_b32 v255, s0, 5
	s_nop 1
	v_writelane_b32 v255, s1, 6
	s_and_saveexec_b64 s[4:5], s[0:1]
	s_cbranch_execz .LBB0_2
	s_add_i32 s1, 0, 0x23fc0
	v_mov_b32_e32 v1, 0
	v_mov_b32_e32 v2, s1
	s_add_i32 s1, 0, 0x23fc4
	ds_write_b32 v2, v1
	v_mov_b32_e32 v2, s1
	ds_write_b32 v2, v1

; #define LAS __attribute__((address_space(3)))
; __device__ __forceinline__ unsigned xb_add(unsigned* p, unsigned v) { return __hip_atomic_fetch_add(p, v, __ATOMIC_RELAXED, __HIP_MEMORY_SCOPE_AGENT); }
; __device__ __forceinline__ unsigned xb_xcc_id() { return (unsigned)__builtin_amdgcn_s_getreg((3 << 11) | 20) & 0xFu; }
; __device__ __forceinline__ XcdBarrier xcd_barrier_post(unsigned* bar, volatile LAS unsigned* st) {
;     XcdBarrier b; b.bar = bar; b.x = xb_xcc_id(); b.st = st;
;     if (threadIdx.x == 0) (void)xb_add(&bar[XB_XCNT(b.x)], 1u);
;     return b;
.LBB0_163:
	s_getreg_b32 s1, hwreg(HW_REG_XCC_ID, 0, 4)
	s_mov_b64 s[4:5], exec
	v_readlane_b32 s2, v255, 5
	v_readlane_b32 s3, v255, 6
	s_and_b64 s[2:3], s[4:5], s[2:3]
	s_mov_b64 exec, s[2:3]
	s_cbranch_execz .LBB0_166
	s_mov_b64 s[6:7], exec
	v_mbcnt_lo_u32_b32 v0, s6, 0
	v_mbcnt_hi_u32_b32 v0, s7, v0
	v_cmp_eq_u32_e32 vcc, 0, v0
	s_and_b64 s[2:3], exec, vcc
	s_mov_b64 exec, s[2:3]
	s_cbranch_execz .LBB0_166
	s_and_b32 s2, s1, 15
	s_lshl_b32 s2, 1, s2
	v_mov_b32_e32 v1, s2
	v_readlane_b32 s2, v255, 0
	s_and_b32 s2, s2, 7
	s_lshl_b32 s2, s2, 2
	v_mov_b32_e32 v0, s2
	global_atomic_or v0, v1, s[80:81]
	s_nop 1
	s_lshl_b32 s1, s1, 8
	s_and_b32 s1, s1, 0xf00
	s_bcnt1_i32_b64 s2, s[6:7]
	v_mov_b32_e32 v0, s1
	v_mov_b32_e32 v1, s2
	global_atomic_add v0, v1, s[80:81] offset:1024

; __global__ void __launch_bounds__(NWAVES * 64, 2) trunk_fwd(Args args) {
;     ...
;     for (int ph = ph0; ph < ph_hi; ++ph) {
;         int kind, l; decode_phase(ph, kind, l); const int li = l >> 1;
.LBB0_169:
	s_or_b64 exec, exec, s[4:5]
	v_readlane_b32 s0, v255, 9
	s_cmp_lg_u32 s0, 2
	s_cbranch_scc1 .Lchk_skip
	v_readlane_b32 s0, v255, 5
	v_readlane_b32 s1, v255, 6
	s_nop 0
	s_and_saveexec_b64 s[2:3], s[0:1]
	s_cbranch_execz .Lchk_end
	v_readlane_b32 s0, v255, 3
	v_readlane_b32 s1, v255, 4
	s_nop 4
	s_load_dwordx2 s[0:1], s[0:1], 0xd0
	v_mov_b32_e32 v10, 0
	s_waitcnt lgkmcnt(0)
	global_load_dword v2, v10, s[0:1] offset:0 sc1
	global_load_dword v3, v10, s[0:1] offset:4 sc1
	global_load_dword v4, v10, s[0:1] offset:8 sc1
	global_load_dword v5, v10, s[0:1] offset:12 sc1
	global_load_dword v6, v10, s[0:1] offset:16 sc1
	global_load_dword v7, v10, s[0:1] offset:20 sc1
	global_load_dword v8, v10, s[0:1] offset:24 sc1
	global_load_dword v9, v10, s[0:1] offset:28 sc1
	s_waitcnt vmcnt(0)
	v_mov_b32_e32 v11, 0
	v_add_u32_e32 v12, -1, v2
	v_and_b32_e32 v12, v12, v2
	v_or_b32_e32 v11, v11, v12
	v_cmp_eq_u32_e32 vcc, 0, v2
	s_nop 1
	v_cndmask_b32_e64 v12, 0, 1, vcc
	v_or_b32_e32 v11, v11, v12
	v_add_u32_e32 v12, -1, v3
	v_and_b32_e32 v12, v12, v3
	v_or_b32_e32 v11, v11, v12
	v_cmp_eq_u32_e32 vcc, 0, v3
	s_nop 1
	v_cndmask_b32_e64 v12, 0, 1, vcc
	v_or_b32_e32 v11, v11, v12
	v_add_u32_e32 v12, -1, v4
	v_and_b32_e32 v12, v12, v4
	v_or_b32_e32 v11, v11, v12
	v_cmp_eq_u32_e32 vcc, 0, v4
	s_nop 1
	v_cndmask_b32_e64 v12, 0, 1, vcc
	v_or_b32_e32 v11, v11, v12
	v_add_u32_e32 v12, -1, v5
	v_and_b32_e32 v12, v12, v5
	v_or_b32_e32 v11, v11, v12
	v_cmp_eq_u32_e32 vcc, 0, v5
	s_nop 1
	v_cndmask_b32_e64 v12, 0, 1, vcc
	v_or_b32_e32 v11, v11, v12
	v_add_u32_e32 v12, -1, v6
	v_and_b32_e32 v12, v12, v6
	v_or_b32_e32 v11, v11, v12
	v_cmp_eq_u32_e32 vcc, 0, v6
	s_nop 1
	v_cndmask_b32_e64 v12, 0, 1, vcc
	v_or_b32_e32 v11, v11, v12
	v_add_u32_e32 v12, -1, v7
	v_and_b32_e32 v12, v12, v7
	v_or_b32_e32 v11, v11, v12
	v_cmp_eq_u32_e32 vcc, 0, v7
	s_nop 1
	v_cndmask_b32_e64 v12, 0, 1, vcc
	v_or_b32_e32 v11, v11, v12
	v_add_u32_e32 v12, -1, v8
	v_and_b32_e32 v12, v12, v8
	v_or_b32_e32 v11, v11, v12
	v_cmp_eq_u32_e32 vcc, 0, v8
	s_nop 1
	v_cndmask_b32_e64 v12, 0, 1, vcc
	v_or_b32_e32 v11, v11, v12
	v_add_u32_e32 v12, -1, v9
	v_and_b32_e32 v12, v12, v9
	v_or_b32_e32 v11, v11, v12
	v_cmp_eq_u32_e32 vcc, 0, v9
	s_nop 1
	v_cndmask_b32_e64 v12, 0, 1, vcc
	v_or_b32_e32 v11, v11, v12
	s_nop 1
	v_readfirstlane_b32 s0, v11
	s_nop 0
	v_writelane_b32 v255, s0, 42
.Lchk_end:
	s_mov_b64 exec, s[2:3]
.Lchk_skip:
	s_mov_b64 s[4:5], 0
	s_waitcnt lgkmcnt(0)
	s_barrier

; __device__ __forceinline__ unsigned cvt_pk_bf16(float lo, float hi) { unsigned r; asm volatile("v_cvt_pk_bf16_f32 %0, %1, %2" : "=v"(r) : "v"(lo), "v"(hi)); return r; }
;     __device__ __forceinline__ void operator()(const f32x4 (&acc)[2][2][4][2], const Unit& u, int wr, int wc, int fr, int fq) const {
;     ...
; #pragma unroll
;         for (int ai = 0; ai < 2; ++ai)
; #pragma unroll
;             for (int m = 0; m < 4; ++m) { const int row = row0 + ai * HALF + m * 16; bf16_t* rowp = O + (size_t)row * ldc + col0;
;                 float sc = 1.f; if (SCALE) sc = rsl ? rsl[((u.pm - pm0) >> 3) * 256 + (row & 255)] : row_rstd(ssq, row);
; #pragma unroll
;                 for (int bj = 0; bj < 2; ++bj) { f32x4 v0 = acc[ai][bj][m][0] * sc, v1 = acc[ai][bj][m][1] * sc;
;                     if (ACT == 1) {
; #pragma unroll
;                         for (int j = 0; j < 4; ++j) { const float a = __builtin_fmaxf(v0[j], 0.f), b = __builtin_fmaxf(v1[j], 0.f); v0[j] = a * a; v1[j] = b * b; } }
;                     u32x4 w; w.x = cvt_pk_bf16(v0[0], v0[1]); w.y = cvt_pk_bf16(v0[2], v0[3]); w.z = cvt_pk_bf16(v1[0], v1[1]); w.w = cvt_pk_bf16(v1[2], v1[3]);
;                     __builtin_nontemporal_store(w, (u32x4*)(rowp + bj * HALF)); } }
.LBB0_245:
	v_lshl_add_u32 v142, s6, 8, v145
	v_ashrrev_i32_e32 v143, 31, v142
	s_and_b64 vcc, exec, s[66:67]
	s_cbranch_vccnz .Lupe_slow
	s_sub_i32 s49, s6, s3
	s_lshl_b32 s49, s49, 7
	s_and_b32 s49, s49, 0xfffffc00
	v_add_u32_e32 v150, s49, v147
	ds_read_b32 v222, v150 offset:0
	ds_read_b32 v224, v150 offset:64
	ds_read_b32 v226, v150 offset:128
	ds_read_b32 v228, v150 offset:192
	ds_read_b32 v230, v150 offset:512
	ds_read_b32 v232, v150 offset:576
	ds_read_b32 v234, v150 offset:640
	ds_read_b32 v236, v150 offset:704
	v_lshl_or_b32 v140, s84, 8, v148
	v_lshlrev_b64 v[152:153], 13, v[142:143]
	v_ashrrev_i32_e32 v141, 31, v140
	v_lshl_add_u64 v[152:153], s[52:53], 0, v[152:153]
	v_lshl_add_u64 v[152:153], v[140:141], 1, v[152:153]
	s_waitcnt lgkmcnt(7)
	v_mov_b32_e32 v154, v152
	v_mov_b32_e32 v155, v153
	v_pk_mul_f32 v[114:115], v[114:115], v[222:223] op_sel_hi:[1,0]
	v_pk_mul_f32 v[116:117], v[116:117], v[222:223] op_sel_hi:[1,0]
	v_pk_mul_f32 v[118:119], v[118:119], v[222:223] op_sel_hi:[1,0]
	v_pk_mul_f32 v[120:121], v[120:121], v[222:223] op_sel_hi:[1,0]
	v_pk_mul_f32 v[122:123], v[122:123], v[222:223] op_sel_hi:[1,0]
	v_pk_mul_f32 v[124:125], v[124:125], v[222:223] op_sel_hi:[1,0]
	v_pk_mul_f32 v[126:127], v[126:127], v[222:223] op_sel_hi:[1,0]
	v_pk_mul_f32 v[128:129], v[128:129], v[222:223] op_sel_hi:[1,0]
	v_max_f32_e32 v114, 0, v114
	v_max_f32_e32 v115, 0, v115
	v_max_f32_e32 v116, 0, v116
	v_max_f32_e32 v117, 0, v117
	v_max_f32_e32 v118, 0, v118
	v_max_f32_e32 v119, 0, v119
	v_max_f32_e32 v120, 0, v120
	v_max_f32_e32 v121, 0, v121
	v_max_f32_e32 v122, 0, v122
	v_max_f32_e32 v123, 0, v123
	v_max_f32_e32 v124, 0, v124
	v_max_f32_e32 v125, 0, v125
	v_max_f32_e32 v126, 0, v126
	v_max_f32_e32 v127, 0, v127
	v_max_f32_e32 v128, 0, v128
	v_max_f32_e32 v129, 0, v129
	v_pk_mul_f32 v[114:115], v[114:115], v[114:115]
	v_pk_mul_f32 v[116:117], v[116:117], v[116:117]
	v_pk_mul_f32 v[118:119], v[118:119], v[118:119]
	v_pk_mul_f32 v[120:121], v[120:121], v[120:121]
	v_pk_mul_f32 v[122:123], v[122:123], v[122:123]
	v_pk_mul_f32 v[124:125], v[124:125], v[124:125]
	v_pk_mul_f32 v[126:127], v[126:127], v[126:127]
	v_pk_mul_f32 v[128:129], v[128:129], v[128:129]
	v_cvt_pk_bf16_f32 v156, v126, v127
	v_cvt_pk_bf16_f32 v157, v128, v129
	v_cvt_pk_bf16_f32 v158, v122, v123
	v_cvt_pk_bf16_f32 v159, v124, v125
	global_store_dwordx4 v[154:155], v[156:159], off nt
	v_cvt_pk_bf16_f32 v160, v118, v119
	v_cvt_pk_bf16_f32 v161, v120, v121
	v_cvt_pk_bf16_f32 v162, v114, v115
	v_cvt_pk_bf16_f32 v163, v116, v117
	global_store_dwordx4 v[154:155], v[160:163], off offset:256 nt
	s_waitcnt lgkmcnt(6)
	v_add_co_u32_e32 v154, vcc, 0x20000, v154
	v_addc_co_u32_e32 v155, vcc, 0, v155, vcc
	v_pk_mul_f32 v[98:99], v[98:99], v[224:225] op_sel_hi:[1,0]
	v_pk_mul_f32 v[100:101], v[100:101], v[224:225] op_sel_hi:[1,0]
	v_pk_mul_f32 v[102:103], v[102:103], v[224:225] op_sel_hi:[1,0]
	v_pk_mul_f32 v[104:105], v[104:105], v[224:225] op_sel_hi:[1,0]
	v_pk_mul_f32 v[106:107], v[106:107], v[224:225] op_sel_hi:[1,0]
	v_pk_mul_f32 v[108:109], v[108:109], v[224:225] op_sel_hi:[1,0]
	v_pk_mul_f32 v[110:111], v[110:111], v[224:225] op_sel_hi:[1,0]
	v_pk_mul_f32 v[112:113], v[112:113], v[224:225] op_sel_hi:[1,0]
	v_max_f32_e32 v98, 0, v98
	v_max_f32_e32 v99, 0, v99
	v_max_f32_e32 v100, 0, v100
	v_max_f32_e32 v101, 0, v101
	v_max_f32_e32 v102, 0, v102
	v_max_f32_e32 v103, 0, v103
	v_max_f32_e32 v104, 0, v104
	v_max_f32_e32 v105, 0, v105
	v_max_f32_e32 v106, 0, v106
	v_max_f32_e32 v107, 0, v107
	v_max_f32_e32 v108, 0, v108
	v_max_f32_e32 v109, 0, v109
	v_max_f32_e32 v110, 0, v110
	v_max_f32_e32 v111, 0, v111
	v_max_f32_e32 v112, 0, v112
	v_max_f32_e32 v113, 0, v113
	v_pk_mul_f32 v[98:99], v[98:99], v[98:99]
	v_pk_mul_f32 v[100:101], v[100:101], v[100:101]
	v_pk_mul_f32 v[102:103], v[102:103], v[102:103]
	v_pk_mul_f32 v[104:105], v[104:105], v[104:105]
	v_pk_mul_f32 v[106:107], v[106:107], v[106:107]
	v_pk_mul_f32 v[108:109], v[108:109], v[108:109]
	v_pk_mul_f32 v[110:111], v[110:111], v[110:111]
	v_pk_mul_f32 v[112:113], v[112:113], v[112:113]
	v_cvt_pk_bf16_f32 v164, v110, v111
	v_cvt_pk_bf16_f32 v165, v112, v113
	v_cvt_pk_bf16_f32 v166, v106, v107
	v_cvt_pk_bf16_f32 v167, v108, v109
	global_store_dwordx4 v[154:155], v[164:167], off nt
	v_cvt_pk_bf16_f32 v168, v102, v103
	v_cvt_pk_bf16_f32 v169, v104, v105
	v_cvt_pk_bf16_f32 v170, v98, v99
	v_cvt_pk_bf16_f32 v171, v100, v101
	global_store_dwordx4 v[154:155], v[168:171], off offset:256 nt
	s_waitcnt lgkmcnt(5)
	v_add_co_u32_e32 v154, vcc, 0x20000, v154
	v_addc_co_u32_e32 v155, vcc, 0, v155, vcc
	v_pk_mul_f32 v[82:83], v[82:83], v[226:227] op_sel_hi:[1,0]
	v_pk_mul_f32 v[84:85], v[84:85], v[226:227] op_sel_hi:[1,0]
	v_pk_mul_f32 v[86:87], v[86:87], v[226:227] op_sel_hi:[1,0]
	v_pk_mul_f32 v[88:89], v[88:89], v[226:227] op_sel_hi:[1,0]
	v_pk_mul_f32 v[90:91], v[90:91], v[226:227] op_sel_hi:[1,0]
	v_pk_mul_f32 v[92:93], v[92:93], v[226:227] op_sel_hi:[1,0]
	v_pk_mul_f32 v[94:95], v[94:95], v[226:227] op_sel_hi:[1,0]
	v_pk_mul_f32 v[96:97], v[96:97], v[226:227] op_sel_hi:[1,0]
	v_max_f32_e32 v82, 0, v82
	v_max_f32_e32 v83, 0, v83
	v_max_f32_e32 v84, 0, v84
	v_max_f32_e32 v85, 0, v85
	v_max_f32_e32 v86, 0, v86
	v_max_f32_e32 v87, 0, v87
	v_max_f32_e32 v88, 0, v88
	v_max_f32_e32 v89, 0, v89
	v_max_f32_e32 v90, 0, v90
	v_max_f32_e32 v91, 0, v91
	v_max_f32_e32 v92, 0, v92
	v_max_f32_e32 v93, 0, v93
	v_max_f32_e32 v94, 0, v94
	v_max_f32_e32 v95, 0, v95
	v_max_f32_e32 v96, 0, v96
	v_max_f32_e32 v97, 0, v97
	v_pk_mul_f32 v[82:83], v[82:83], v[82:83]
	v_pk_mul_f32 v[84:85], v[84:85], v[84:85]
	v_pk_mul_f32 v[86:87], v[86:87], v[86:87]
	v_pk_mul_f32 v[88:89], v[88:89], v[88:89]
	v_pk_mul_f32 v[90:91], v[90:91], v[90:91]
	v_pk_mul_f32 v[92:93], v[92:93], v[92:93]
	v_pk_mul_f32 v[94:95], v[94:95], v[94:95]
	v_pk_mul_f32 v[96:97], v[96:97], v[96:97]
	v_cvt_pk_bf16_f32 v156, v94, v95
	v_cvt_pk_bf16_f32 v157, v96, v97
	v_cvt_pk_bf16_f32 v158, v90, v91
	v_cvt_pk_bf16_f32 v159, v92, v93
	global_store_dwordx4 v[154:155], v[156:159], off nt
	v_cvt_pk_bf16_f32 v160, v86, v87
	v_cvt_pk_bf16_f32 v161, v88, v89
	v_cvt_pk_bf16_f32 v162, v82, v83
	v_cvt_pk_bf16_f32 v163, v84, v85
	global_store_dwordx4 v[154:155], v[160:163], off offset:256 nt
	s_waitcnt lgkmcnt(4)
; __device__ __forceinline__ unsigned cvt_pk_bf16(float lo, float hi) { unsigned r; asm volatile("v_cvt_pk_bf16_f32 %0, %1, %2" : "=v"(r) : "v"(lo), "v"(hi)); return r; }
;     __device__ __forceinline__ void operator()(const f32x4 (&acc)[2][2][4][2], const Unit& u, int wr, int wc, int fr, int fq) const {
;     ...
; #pragma unroll
;         for (int ai = 0; ai < 2; ++ai)
; #pragma unroll
;             for (int m = 0; m < 4; ++m) { const int row = row0 + ai * HALF + m * 16; bf16_t* rowp = O + (size_t)row * ldc + col0;
;                 float sc = 1.f; if (SCALE) sc = rsl ? rsl[((u.pm - pm0) >> 3) * 256 + (row & 255)] : row_rstd(ssq, row);
; #pragma unroll
;                 for (int bj = 0; bj < 2; ++bj) { f32x4 v0 = acc[ai][bj][m][0] * sc, v1 = acc[ai][bj][m][1] * sc;
;                     if (ACT == 1) {
; #pragma unroll
;                         for (int j = 0; j < 4; ++j) { const float a = __builtin_fmaxf(v0[j], 0.f), b = __builtin_fmaxf(v1[j], 0.f); v0[j] = a * a; v1[j] = b * b; } }
;                     u32x4 w; w.x = cvt_pk_bf16(v0[0], v0[1]); w.y = cvt_pk_bf16(v0[2], v0[3]); w.z = cvt_pk_bf16(v1[0], v1[1]); w.w = cvt_pk_bf16(v1[2], v1[3]);
;                     __builtin_nontemporal_store(w, (u32x4*)(rowp + bj * HALF)); } }
	v_add_co_u32_e32 v154, vcc, 0x20000, v154
	v_addc_co_u32_e32 v155, vcc, 0, v155, vcc
	v_pk_mul_f32 v[66:67], v[66:67], v[228:229] op_sel_hi:[1,0]
	v_pk_mul_f32 v[68:69], v[68:69], v[228:229] op_sel_hi:[1,0]
	v_pk_mul_f32 v[70:71], v[70:71], v[228:229] op_sel_hi:[1,0]
	v_pk_mul_f32 v[72:73], v[72:73], v[228:229] op_sel_hi:[1,0]
	v_pk_mul_f32 v[74:75], v[74:75], v[228:229] op_sel_hi:[1,0]
	v_pk_mul_f32 v[76:77], v[76:77], v[228:229] op_sel_hi:[1,0]
	v_pk_mul_f32 v[78:79], v[78:79], v[228:229] op_sel_hi:[1,0]
	v_pk_mul_f32 v[80:81], v[80:81], v[228:229] op_sel_hi:[1,0]
	v_max_f32_e32 v66, 0, v66
	v_max_f32_e32 v67, 0, v67
	v_max_f32_e32 v68, 0, v68
	v_max_f32_e32 v69, 0, v69
	v_max_f32_e32 v70, 0, v70
	v_max_f32_e32 v71, 0, v71
	v_max_f32_e32 v72, 0, v72
	v_max_f32_e32 v73, 0, v73
	v_max_f32_e32 v74, 0, v74
	v_max_f32_e32 v75, 0, v75
	v_max_f32_e32 v76, 0, v76
	v_max_f32_e32 v77, 0, v77
	v_max_f32_e32 v78, 0, v78
	v_max_f32_e32 v79, 0, v79
	v_max_f32_e32 v80, 0, v80
	v_max_f32_e32 v81, 0, v81
	v_pk_mul_f32 v[66:67], v[66:67], v[66:67]
	v_pk_mul_f32 v[68:69], v[68:69], v[68:69]
	v_pk_mul_f32 v[70:71], v[70:71], v[70:71]
	v_pk_mul_f32 v[72:73], v[72:73], v[72:73]
	v_pk_mul_f32 v[74:75], v[74:75], v[74:75]
	v_pk_mul_f32 v[76:77], v[76:77], v[76:77]
	v_pk_mul_f32 v[78:79], v[78:79], v[78:79]
	v_pk_mul_f32 v[80:81], v[80:81], v[80:81]
	v_cvt_pk_bf16_f32 v164, v78, v79
	v_cvt_pk_bf16_f32 v165, v80, v81
	v_cvt_pk_bf16_f32 v166, v74, v75
	v_cvt_pk_bf16_f32 v167, v76, v77
	global_store_dwordx4 v[154:155], v[164:167], off nt
	v_cvt_pk_bf16_f32 v168, v70, v71
	v_cvt_pk_bf16_f32 v169, v72, v73
	v_cvt_pk_bf16_f32 v170, v66, v67
	v_cvt_pk_bf16_f32 v171, v68, v69
	global_store_dwordx4 v[154:155], v[168:171], off offset:256 nt
	s_waitcnt lgkmcnt(3)
	v_add_co_u32_e32 v154, vcc, 0x100000, v152
	v_addc_co_u32_e32 v155, vcc, 0, v153, vcc
	v_pk_mul_f32 v[50:51], v[50:51], v[230:231] op_sel_hi:[1,0]
	v_pk_mul_f32 v[52:53], v[52:53], v[230:231] op_sel_hi:[1,0]
	v_pk_mul_f32 v[54:55], v[54:55], v[230:231] op_sel_hi:[1,0]
	v_pk_mul_f32 v[56:57], v[56:57], v[230:231] op_sel_hi:[1,0]
	v_pk_mul_f32 v[58:59], v[58:59], v[230:231] op_sel_hi:[1,0]
	v_pk_mul_f32 v[60:61], v[60:61], v[230:231] op_sel_hi:[1,0]
	v_pk_mul_f32 v[62:63], v[62:63], v[230:231] op_sel_hi:[1,0]
	v_pk_mul_f32 v[64:65], v[64:65], v[230:231] op_sel_hi:[1,0]
	v_max_f32_e32 v50, 0, v50
	v_max_f32_e32 v51, 0, v51
	v_max_f32_e32 v52, 0, v52
	v_max_f32_e32 v53, 0, v53
	v_max_f32_e32 v54, 0, v54
	v_max_f32_e32 v55, 0, v55
	v_max_f32_e32 v56, 0, v56
	v_max_f32_e32 v57, 0, v57
	v_max_f32_e32 v58, 0, v58
	v_max_f32_e32 v59, 0, v59
	v_max_f32_e32 v60, 0, v60
	v_max_f32_e32 v61, 0, v61
	v_max_f32_e32 v62, 0, v62
	v_max_f32_e32 v63, 0, v63
	v_max_f32_e32 v64, 0, v64
	v_max_f32_e32 v65, 0, v65
	v_pk_mul_f32 v[50:51], v[50:51], v[50:51]
	v_pk_mul_f32 v[52:53], v[52:53], v[52:53]
	v_pk_mul_f32 v[54:55], v[54:55], v[54:55]
	v_pk_mul_f32 v[56:57], v[56:57], v[56:57]
	v_pk_mul_f32 v[58:59], v[58:59], v[58:59]
	v_pk_mul_f32 v[60:61], v[60:61], v[60:61]
	v_pk_mul_f32 v[62:63], v[62:63], v[62:63]
	v_pk_mul_f32 v[64:65], v[64:65], v[64:65]
	v_cvt_pk_bf16_f32 v156, v62, v63
	v_cvt_pk_bf16_f32 v157, v64, v65
	v_cvt_pk_bf16_f32 v158, v58, v59
	v_cvt_pk_bf16_f32 v159, v60, v61
	global_store_dwordx4 v[154:155], v[156:159], off nt
	v_cvt_pk_bf16_f32 v160, v54, v55
	v_cvt_pk_bf16_f32 v161, v56, v57
	v_cvt_pk_bf16_f32 v162, v50, v51
	v_cvt_pk_bf16_f32 v163, v52, v53
	global_store_dwordx4 v[154:155], v[160:163], off offset:256 nt
	s_waitcnt lgkmcnt(2)
	v_add_co_u32_e32 v154, vcc, 0x20000, v154
	v_addc_co_u32_e32 v155, vcc, 0, v155, vcc
	v_pk_mul_f32 v[34:35], v[34:35], v[232:233] op_sel_hi:[1,0]
	v_pk_mul_f32 v[36:37], v[36:37], v[232:233] op_sel_hi:[1,0]
	v_pk_mul_f32 v[38:39], v[38:39], v[232:233] op_sel_hi:[1,0]
	v_pk_mul_f32 v[40:41], v[40:41], v[232:233] op_sel_hi:[1,0]
	v_pk_mul_f32 v[42:43], v[42:43], v[232:233] op_sel_hi:[1,0]
	v_pk_mul_f32 v[44:45], v[44:45], v[232:233] op_sel_hi:[1,0]
	v_pk_mul_f32 v[46:47], v[46:47], v[232:233] op_sel_hi:[1,0]
	v_pk_mul_f32 v[48:49], v[48:49], v[232:233] op_sel_hi:[1,0]
	v_max_f32_e32 v34, 0, v34
	v_max_f32_e32 v35, 0, v35
	v_max_f32_e32 v36, 0, v36
	v_max_f32_e32 v37, 0, v37
	v_max_f32_e32 v38, 0, v38
	v_max_f32_e32 v39, 0, v39
	v_max_f32_e32 v40, 0, v40
	v_max_f32_e32 v41, 0, v41
	v_max_f32_e32 v42, 0, v42
	v_max_f32_e32 v43, 0, v43
	v_max_f32_e32 v44, 0, v44
	v_max_f32_e32 v45, 0, v45
	v_max_f32_e32 v46, 0, v46
	v_max_f32_e32 v47, 0, v47
	v_max_f32_e32 v48, 0, v48
	v_max_f32_e32 v49, 0, v49
	v_pk_mul_f32 v[34:35], v[34:35], v[34:35]
	v_pk_mul_f32 v[36:37], v[36:37], v[36:37]
	v_pk_mul_f32 v[38:39], v[38:39], v[38:39]
	v_pk_mul_f32 v[40:41], v[40:41], v[40:41]
	v_pk_mul_f32 v[42:43], v[42:43], v[42:43]
	v_pk_mul_f32 v[44:45], v[44:45], v[44:45]
	v_pk_mul_f32 v[46:47], v[46:47], v[46:47]
	v_pk_mul_f32 v[48:49], v[48:49], v[48:49]
	v_cvt_pk_bf16_f32 v164, v46, v47
	v_cvt_pk_bf16_f32 v165, v48, v49
	v_cvt_pk_bf16_f32 v166, v42, v43
	v_cvt_pk_bf16_f32 v167, v44, v45
	global_store_dwordx4 v[154:155], v[164:167], off nt
	v_cvt_pk_bf16_f32 v168, v38, v39
	v_cvt_pk_bf16_f32 v169, v40, v41
	v_cvt_pk_bf16_f32 v170, v34, v35
	v_cvt_pk_bf16_f32 v171, v36, v37
	global_store_dwordx4 v[154:155], v[168:171], off offset:256 nt
	s_waitcnt lgkmcnt(1)
; __device__ __forceinline__ unsigned cvt_pk_bf16(float lo, float hi) { unsigned r; asm volatile("v_cvt_pk_bf16_f32 %0, %1, %2" : "=v"(r) : "v"(lo), "v"(hi)); return r; }
; __device__ __forceinline__ float row_rstd(const float* ssq, int row) {
;     const f32x4* p = (const f32x4*)(ssq + (size_t)row * 16);
;     const f32x4 a = p[0], b = p[1], c = p[2], d = p[3];
;     const float s = (((a[0] + a[1]) + (a[2] + a[3])) + ((b[0] + b[1]) + (b[2] + b[3]))) + (((c[0] + c[1]) + (c[2] + c[3])) + ((d[0] + d[1]) + (d[2] + d[3])));
;     return __builtin_amdgcn_rsqf(s * (1.0f / 1024.0f) + 1e-6f);
; }
;     __device__ __forceinline__ void operator()(const f32x4 (&acc)[2][2][4][2], const Unit& u, int wr, int wc, int fr, int fq) const {
;     ...
; #pragma unroll
;         for (int ai = 0; ai < 2; ++ai)
; #pragma unroll
;             for (int m = 0; m < 4; ++m) { const int row = row0 + ai * HALF + m * 16; bf16_t* rowp = O + (size_t)row * ldc + col0;
;                 float sc = 1.f; if (SCALE) sc = rsl ? rsl[((u.pm - pm0) >> 3) * 256 + (row & 255)] : row_rstd(ssq, row);
; #pragma unroll
;                 for (int bj = 0; bj < 2; ++bj) { f32x4 v0 = acc[ai][bj][m][0] * sc, v1 = acc[ai][bj][m][1] * sc;
;                     if (ACT == 1) {
; #pragma unroll
;                         for (int j = 0; j < 4; ++j) { const float a = __builtin_fmaxf(v0[j], 0.f), b = __builtin_fmaxf(v1[j], 0.f); v0[j] = a * a; v1[j] = b * b; } }
;                     u32x4 w; w.x = cvt_pk_bf16(v0[0], v0[1]); w.y = cvt_pk_bf16(v0[2], v0[3]); w.z = cvt_pk_bf16(v1[0], v1[1]); w.w = cvt_pk_bf16(v1[2], v1[3]);
;                     __builtin_nontemporal_store(w, (u32x4*)(rowp + bj * HALF)); } }
	v_add_co_u32_e32 v154, vcc, 0x20000, v154
	v_addc_co_u32_e32 v155, vcc, 0, v155, vcc
	v_pk_mul_f32 v[18:19], v[18:19], v[234:235] op_sel_hi:[1,0]
	v_pk_mul_f32 v[20:21], v[20:21], v[234:235] op_sel_hi:[1,0]
	v_pk_mul_f32 v[22:23], v[22:23], v[234:235] op_sel_hi:[1,0]
	v_pk_mul_f32 v[24:25], v[24:25], v[234:235] op_sel_hi:[1,0]
	v_pk_mul_f32 v[26:27], v[26:27], v[234:235] op_sel_hi:[1,0]
	v_pk_mul_f32 v[28:29], v[28:29], v[234:235] op_sel_hi:[1,0]
	v_pk_mul_f32 v[30:31], v[30:31], v[234:235] op_sel_hi:[1,0]
	v_pk_mul_f32 v[32:33], v[32:33], v[234:235] op_sel_hi:[1,0]
	v_max_f32_e32 v18, 0, v18
	v_max_f32_e32 v19, 0, v19
	v_max_f32_e32 v20, 0, v20
	v_max_f32_e32 v21, 0, v21
	v_max_f32_e32 v22, 0, v22
	v_max_f32_e32 v23, 0, v23
	v_max_f32_e32 v24, 0, v24
	v_max_f32_e32 v25, 0, v25
	v_max_f32_e32 v26, 0, v26
	v_max_f32_e32 v27, 0, v27
	v_max_f32_e32 v28, 0, v28
	v_max_f32_e32 v29, 0, v29
	v_max_f32_e32 v30, 0, v30
	v_max_f32_e32 v31, 0, v31
	v_max_f32_e32 v32, 0, v32
	v_max_f32_e32 v33, 0, v33
	v_pk_mul_f32 v[18:19], v[18:19], v[18:19]
	v_pk_mul_f32 v[20:21], v[20:21], v[20:21]
	v_pk_mul_f32 v[22:23], v[22:23], v[22:23]
	v_pk_mul_f32 v[24:25], v[24:25], v[24:25]
	v_pk_mul_f32 v[26:27], v[26:27], v[26:27]
	v_pk_mul_f32 v[28:29], v[28:29], v[28:29]
	v_pk_mul_f32 v[30:31], v[30:31], v[30:31]
	v_pk_mul_f32 v[32:33], v[32:33], v[32:33]
	v_cvt_pk_bf16_f32 v156, v30, v31
	v_cvt_pk_bf16_f32 v157, v32, v33
	v_cvt_pk_bf16_f32 v158, v26, v27
	v_cvt_pk_bf16_f32 v159, v28, v29
	global_store_dwordx4 v[154:155], v[156:159], off nt
	v_cvt_pk_bf16_f32 v160, v22, v23
	v_cvt_pk_bf16_f32 v161, v24, v25
	v_cvt_pk_bf16_f32 v162, v18, v19
	v_cvt_pk_bf16_f32 v163, v20, v21
	global_store_dwordx4 v[154:155], v[160:163], off offset:256 nt
	s_waitcnt lgkmcnt(0)
	v_add_co_u32_e32 v154, vcc, 0x20000, v154
	v_addc_co_u32_e32 v155, vcc, 0, v155, vcc
	v_pk_mul_f32 v[2:3], v[2:3], v[236:237] op_sel_hi:[1,0]
	v_pk_mul_f32 v[4:5], v[4:5], v[236:237] op_sel_hi:[1,0]
	v_pk_mul_f32 v[6:7], v[6:7], v[236:237] op_sel_hi:[1,0]
	v_pk_mul_f32 v[8:9], v[8:9], v[236:237] op_sel_hi:[1,0]
	v_pk_mul_f32 v[10:11], v[10:11], v[236:237] op_sel_hi:[1,0]
	v_pk_mul_f32 v[12:13], v[12:13], v[236:237] op_sel_hi:[1,0]
	v_pk_mul_f32 v[14:15], v[14:15], v[236:237] op_sel_hi:[1,0]
	v_pk_mul_f32 v[16:17], v[16:17], v[236:237] op_sel_hi:[1,0]
	v_max_f32_e32 v2, 0, v2
	v_max_f32_e32 v3, 0, v3
	v_max_f32_e32 v4, 0, v4
	v_max_f32_e32 v5, 0, v5
	v_max_f32_e32 v6, 0, v6
	v_max_f32_e32 v7, 0, v7
	v_max_f32_e32 v8, 0, v8
	v_max_f32_e32 v9, 0, v9
	v_max_f32_e32 v10, 0, v10
	v_max_f32_e32 v11, 0, v11
	v_max_f32_e32 v12, 0, v12
	v_max_f32_e32 v13, 0, v13
	v_max_f32_e32 v14, 0, v14
	v_max_f32_e32 v15, 0, v15
	v_max_f32_e32 v16, 0, v16
	v_max_f32_e32 v17, 0, v17
	v_pk_mul_f32 v[2:3], v[2:3], v[2:3]
	v_pk_mul_f32 v[4:5], v[4:5], v[4:5]
	v_pk_mul_f32 v[6:7], v[6:7], v[6:7]
	v_pk_mul_f32 v[8:9], v[8:9], v[8:9]
	v_pk_mul_f32 v[10:11], v[10:11], v[10:11]
	v_pk_mul_f32 v[12:13], v[12:13], v[12:13]
	v_pk_mul_f32 v[14:15], v[14:15], v[14:15]
	v_pk_mul_f32 v[16:17], v[16:17], v[16:17]
	v_cvt_pk_bf16_f32 v164, v14, v15
	v_cvt_pk_bf16_f32 v165, v16, v17
	v_cvt_pk_bf16_f32 v166, v10, v11
	v_cvt_pk_bf16_f32 v167, v12, v13
	global_store_dwordx4 v[154:155], v[164:167], off nt
	v_cvt_pk_bf16_f32 v168, v6, v7
	v_cvt_pk_bf16_f32 v169, v8, v9
	v_cvt_pk_bf16_f32 v170, v2, v3
	v_cvt_pk_bf16_f32 v171, v4, v5
	global_store_dwordx4 v[154:155], v[168:171], off offset:256 nt
	s_andn2_b64 vcc, exec, s[4:5]
	s_mov_b64 s[4:5], -1
	s_cbranch_vccnz .LBB0_234
	s_branch .Lupe_tail
.Lupe_slow:
	s_mov_b64 s[86:87], -1
	s_and_b64 vcc, exec, s[66:67]
	s_cbranch_vccz .LBB0_247
	v_lshlrev_b64 v[140:141], 6, v[142:143]
	v_lshl_add_u64 v[140:141], s[56:57], 0, v[140:141]
	global_load_dwordx4 v[150:153], v[140:141], off
	global_load_dwordx4 v[154:157], v[140:141], off offset:32
	global_load_dwordx4 v[158:161], v[140:141], off offset:16
	global_load_dwordx4 v[162:165], v[140:141], off offset:48
	s_mov_b64 s[86:87], 0
	s_waitcnt vmcnt(0)
	v_mov_b32_e32 v140, v150
	v_mov_b32_e32 v141, v154
	v_mov_b32_e32 v154, v151
	v_mov_b32_e32 v150, v152
	v_mov_b32_e32 v151, v156
	v_mov_b32_e32 v156, v153
	v_mov_b32_e32 v152, v158
	v_mov_b32_e32 v153, v162
	v_mov_b32_e32 v162, v159
	v_mov_b32_e32 v158, v160
	v_mov_b32_e32 v159, v164
	v_mov_b32_e32 v164, v161
	v_pk_add_f32 v[140:141], v[140:141], v[154:155]
	v_pk_add_f32 v[150:151], v[150:151], v[156:157]
	v_pk_add_f32 v[152:153], v[152:153], v[162:163]
	v_pk_add_f32 v[154:155], v[158:159], v[164:165]
	v_pk_add_f32 v[140:141], v[140:141], v[150:151]
	v_pk_add_f32 v[150:151], v[152:153], v[154:155]
	s_nop 0
	v_pk_add_f32 v[140:141], v[140:141], v[150:151]
	s_nop 0
	v_add_f32_e32 v140, v140, v141
	v_fmamk_f32 v140, v140, 0x3a800000, v207
	v_rsq_f32_e32 v144, v140

; #define PG8_BAR __builtin_amdgcn_s_barrier()
; template <class Epi, class Sched, bool ALIGN_EPI = false, bool SP2 = false>
; __device__ __forceinline__ void gemm_phase(PG8_LAS unsigned char* lds, const Gemm g, const Sched& S, const Epi& E) {
;     ...
;         cur = nxt; cA = nA; cB = nB; ++ui;
;         if constexpr (ALIGN_EPI) { if (wr == 1) PG8_BAR; }
.Lupe_tail:
	s_andn2_b64 vcc, exec, s[72:73]
	s_cbranch_vccnz .LBB0_233
	s_barrier
	s_branch .LBB0_233

; __device__ __forceinline__ unsigned xb_ld(unsigned* p)              { return __hip_atomic_load(p, __ATOMIC_RELAXED, __HIP_MEMORY_SCOPE_AGENT); }
; __device__ __forceinline__ unsigned xb_add(unsigned* p, unsigned v) { return __hip_atomic_fetch_add(p, v, __ATOMIC_RELAXED, __HIP_MEMORY_SCOPE_AGENT); }
; #define XB_SPIN(cond, bar) do { unsigned _sp = 0; while (cond) { __builtin_amdgcn_s_sleep(1); \
;     if ((++_sp & 255u) == 0u) { if (xb_ld(&(bar)[XB_TMO])) break; if (_sp > XB_SPIN_CAP) { atomicAdd(&(bar)[XB_TMO], 1u); break; } } } } while (0)
; __device__ __forceinline__ void xcd_barrier(const XcdBarrier& b) {
;     asm volatile("s_waitcnt vmcnt(0)" ::: "memory");
;     __syncthreads();
;     if (threadIdx.x == 0) {
;         unsigned* bar = b.bar;
;         __builtin_amdgcn_s_waitcnt(0);
;         unsigned nloc = b.st[0], nx = b.st[1];
;         if (nloc == 0u) { xcd_barrier_complete(bar, b.x, nloc, nx); b.st[0] = nloc; b.st[1] = nx; }
;         const unsigned old = xb_add(&bar[XB_XSUB(b.x)], 1u);
;         const unsigned gen = old / nloc;
;         if (old + 1u == (gen + 1u) * nloc) {
;             __builtin_amdgcn_fence(__ATOMIC_RELEASE, "agent");
;             asm volatile("s_waitcnt vmcnt(0)" ::: "memory");
;             const unsigned og = xb_add(&bar[XB_TOP], 1u);
;             const unsigned tg = og / nx;
;             if (og + 1u == (tg + 1u) * nx) xb_add(&bar[XB_TOPGEN], 1u);
;             else XB_SPIN(xb_ld(&bar[XB_TOPGEN]) == tg, bar);
;             __builtin_amdgcn_fence(__ATOMIC_ACQUIRE, "agent");
;             xb_add(&bar[XB_XGEN(b.x)], 1u);
.LBB0_652:
	s_andn2_saveexec_b64 s[8:9], s[8:9]
	s_cbranch_execz .LBB0_169
	s_mov_b64 s[8:9], exec
	s_waitcnt lgkmcnt(0)
	v_readlane_b32 s0, v255, 9
	s_sub_u32 s0, s0, 3
	s_cmp_lt_u32 s0, 26
	s_cbranch_scc0 .Lxb_global
	v_readlane_b32 s0, v255, 42
	s_cmp_eq_u32 s0, 0
	s_cbranch_scc1 .Lxb_local
.Lxb_global:
	buffer_wbl2 sc1
	s_waitcnt lgkmcnt(0)
	s_waitcnt vmcnt(0)
	v_mbcnt_lo_u32_b32 v2, s8, 0
	v_mbcnt_hi_u32_b32 v2, s9, v2
	v_cmp_eq_u32_e32 vcc, 0, v2
	s_and_saveexec_b64 s[16:17], vcc
	s_cbranch_execz .LBB0_655
	s_bcnt1_i32_b64 s0, s[8:9]
	v_mov_b32_e32 v3, s0
	v_mov_b32_e32 v4, 0x3000
	global_atomic_add v3, v4, v3, s[18:19] offset:1024 sc0
